# P0: s_setprio 1 for the odd (weight-item) waves on top of the clean config
# baseline (speedup 1.0000x reference)
.LBB0_21:
	s_lshr_b32 s5, s34, 6
	s_lshl_b32 s4, s3, 3
	s_add_i32 s4, s4, s5
	s_lshl_b32 s72, s30, 3
	s_add_u32 s76, s58, 0x200000
	s_addc_u32 s77, s59, 0
	v_writelane_b32 v244, s5, 16
	s_add_u32 s74, s58, 0x800000
	v_writelane_b32 v244, s4, 17
	s_addc_u32 s75, s59, 0
	v_and_b32_e32 v203, 63, v209
	v_writelane_b32 v244, s5, 18
	s_add_u32 s4, s58, 0xa00000
	s_addc_u32 s5, s59, 0
	v_writelane_b32 v244, s4, 19
	s_nop 1
	v_writelane_b32 v244, s5, 20
	s_add_u32 s4, s58, 0xb00000
	s_addc_u32 s5, s59, 0
	s_add_u32 s66, s58, 0xd00000
	v_writelane_b32 v244, s4, 21
	s_addc_u32 s67, s59, 0
	s_nop 0
	v_writelane_b32 v244, s5, 22
	s_add_u32 s4, s58, 0xf00000
	s_addc_u32 s5, s59, 0
	s_add_u32 s94, s58, 0x1700000
	s_addc_u32 s95, s59, 0
	s_add_u32 s60, s58, 0x2000000
	v_writelane_b32 v244, s4, 23
	s_addc_u32 s61, s59, 0
	s_nop 0
	v_writelane_b32 v244, s5, 24
	s_add_u32 s4, s58, 0x1f00000
	s_addc_u32 s5, s59, 0
	v_writelane_b32 v244, s4, 25
	s_cmp_lt_i32 s28, 1
	s_nop 0
	v_writelane_b32 v244, s5, 26
	s_cselect_b64 s[4:5], -1, 0
	s_cmp_gt_i32 s29, 0
	s_cselect_b64 s[6:7], -1, 0
	v_writelane_b32 v244, s28, 27
	s_and_b64 s[78:79], s[4:5], s[6:7]
	s_andn2_b64 vcc, exec, s[78:79]
	v_writelane_b32 v244, s29, 28
	v_writelane_b32 v244, s30, 29
	v_writelane_b32 v244, s31, 30
	s_cbranch_vccnz .LBB0_147
	s_bitcmp0_b32 s34, 6
	s_mov_b64 s[4:5], -1
	s_cbranch_scc1 .LBB0_139
	s_setprio 1

.LBB0_147:
	s_setprio 0
	s_cmp_gt_i32 s29, 1
	s_cselect_b64 s[0:1], -1, 0
	s_and_b64 s[4:5], s[78:79], s[0:1]
	v_readlane_b32 s78, v244, 21
	s_andn2_b64 vcc, exec, s[4:5]
	v_readlane_b32 s79, v244, 22
	s_cbranch_vccnz .LBB0_197
	s_waitcnt vmcnt(0)
	v_cmp_eq_u32_e32 vcc, 0, v209
	s_barrier
	s_and_saveexec_b64 s[4:5], vcc
	s_cbranch_execz .LBB0_196
	s_add_i32 s6, 0, 0x20000
	v_mov_b32_e32 v0, s6
	s_waitcnt vmcnt(0) expcnt(0) lgkmcnt(0)
	ds_read_b32 v2, v0
	s_add_i32 s6, 0, 0x20004
	v_mov_b32_e32 v0, s6
	ds_read_b32 v0, v0
	s_waitcnt lgkmcnt(1)
	v_cmp_ne_u32_e32 vcc, 0, v2
	s_cbranch_vccnz .LBB0_164
	s_add_u32 s6, s58, 0x1000
	s_addc_u32 s7, s59, 0
	s_add_u32 s8, s58, 0x1100
	s_addc_u32 s9, s59, 0
	s_add_u32 s10, s58, 0x1200
	s_addc_u32 s11, s59, 0
	s_mul_i32 s24, s31, s97
	s_add_u32 s12, s58, 0x1300
	s_mul_i32 s24, s24, s30
	s_addc_u32 s13, s59, 0
	s_mov_b32 s25, 1
	v_mov_b32_e32 v16, 0
	s_branch .LBB0_152
